# attention loop: loop-carried scalar updates moved into the MFMA result wait-state shadow (s_nop 8 -> 3)
# baseline (speedup 1.0000x reference)
.LBB0_392:
	s_setprio 1
	s_or_b64 exec, exec, s[44:45]
	s_add_i32 s63, s63, 32
	v_cmp_eq_u32_e32 vcc, s64, v150
	v_lshl_add_u64 v[138:139], v[138:139], 0, s[38:39]
	s_or_b64 s[40:41], vcc, s[40:41]
	s_mov_b32 s65, s64
	s_nop 3
	v_max_f32_e32 v48, v33, v33
	v_max_f32_e32 v49, v32, v32
	v_max_f32_e32 v48, v49, v48
	v_max3_f32 v48, v48, v34, v35
	v_max3_f32 v48, v48, v36, v37
	v_max3_f32 v48, v48, v38, v39
	v_max3_f32 v48, v48, v40, v41
	v_max3_f32 v48, v48, v42, v43
	v_max3_f32 v48, v48, v44, v45
	v_max3_f32 v49, v48, v46, v47
	ds_bpermute_b32 v50, v223, v49
	s_waitcnt lgkmcnt(0)
	v_max3_f32 v49, v156, v49, v50
	v_sub_f32_e32 v32, v32, v49
	v_exp_f32_e32 v50, v32
	v_sub_f32_e32 v32, v33, v49
	v_exp_f32_e32 v51, v32
	v_sub_f32_e32 v34, v34, v49
	v_exp_f32_e32 v52, v34
	v_sub_f32_e32 v34, v35, v49
	v_exp_f32_e32 v53, v34
	v_sub_f32_e32 v34, v36, v49
	v_add_f32_e32 v33, 0, v50
	v_exp_f32_e32 v54, v34
	v_sub_f32_e32 v34, v37, v49
	v_add_f32_e32 v33, v51, v33
	v_exp_f32_e32 v55, v34
	v_sub_f32_e32 v34, v38, v49
	v_add_f32_e32 v33, v52, v33
	v_exp_f32_e32 v56, v34
	v_sub_f32_e32 v34, v39, v49
	v_add_f32_e32 v33, v53, v33
	v_exp_f32_e32 v39, v34
	v_sub_f32_e32 v34, v40, v49
	v_add_f32_e32 v33, v54, v33
	v_exp_f32_e32 v57, v34
	v_sub_f32_e32 v34, v41, v49
	v_add_f32_e32 v33, v55, v33
	v_exp_f32_e32 v58, v34
	v_add_f32_e32 v33, v56, v33
	v_add_f32_e32 v33, v39, v33
	v_add_f32_e32 v33, v57, v33
	v_add_f32_e32 v59, v58, v33
	v_sub_f32_e32 v33, v42, v49
	v_exp_f32_e32 v60, v33
	v_sub_f32_e32 v33, v43, v49
	v_sub_f32_e32 v32, v156, v49
	v_exp_f32_e32 v61, v33
	v_sub_f32_e32 v33, v44, v49
	v_exp_f32_e32 v62, v33
	v_sub_f32_e32 v33, v45, v49
	v_exp_f32_e32 v44, v32
	v_sub_f32_e32 v32, v46, v49
	v_cvt_pk_bf16_f32 v36, v50, v51
	v_exp_f32_e32 v45, v33
	v_exp_f32_e32 v46, v32
	ds_read2_b64 v[32:35], v224 offset0:64 offset1:66
	ds_read2_b64 v[40:43], v225 offset0:128 offset1:130
	v_pk_mul_f32 v[30:31], v[30:31], v[44:45] op_sel_hi:[1,0]
	v_pk_mul_f32 v[28:29], v[28:29], v[44:45] op_sel_hi:[1,0]
	v_pk_mul_f32 v[26:27], v[26:27], v[44:45] op_sel_hi:[1,0]
	v_pk_mul_f32 v[24:25], v[24:25], v[44:45] op_sel_hi:[1,0]
	v_pk_mul_f32 v[22:23], v[22:23], v[44:45] op_sel_hi:[1,0]
	v_pk_mul_f32 v[20:21], v[20:21], v[44:45] op_sel_hi:[1,0]
	v_pk_mul_f32 v[18:19], v[18:19], v[44:45] op_sel_hi:[1,0]
	v_pk_mul_f32 v[16:17], v[16:17], v[44:45] op_sel_hi:[1,0]
	v_pk_mul_f32 v[14:15], v[14:15], v[44:45] op_sel_hi:[1,0]
	v_pk_mul_f32 v[12:13], v[12:13], v[44:45] op_sel_hi:[1,0]
	v_cvt_pk_bf16_f32 v37, v52, v53
	v_cvt_pk_bf16_f32 v38, v54, v55
	v_cvt_pk_bf16_f32 v39, v56, v39
	v_pk_mul_f32 v[10:11], v[10:11], v[44:45] op_sel_hi:[1,0]
	v_pk_mul_f32 v[8:9], v[8:9], v[44:45] op_sel_hi:[1,0]
	v_pk_mul_f32 v[6:7], v[6:7], v[44:45] op_sel_hi:[1,0]
	v_pk_mul_f32 v[4:5], v[4:5], v[44:45] op_sel_hi:[1,0]
	v_pk_mul_f32 v[2:3], v[2:3], v[44:45] op_sel_hi:[1,0]
	v_pk_mul_f32 v[0:1], v[0:1], v[44:45] op_sel_hi:[1,0]
	s_waitcnt lgkmcnt(1)
	v_mfma_f32_32x32x16_bf16 v[16:31], v[32:35], v[36:39], v[16:31]
	ds_read2_b64 v[32:35], v224 offset0:68 offset1:70
	v_mov_b32_e32 v156, v49
	s_waitcnt lgkmcnt(1)
	v_mfma_f32_32x32x16_bf16 v[0:15], v[40:43], v[36:39], v[0:15]
	ds_read2_b64 v[40:43], v225 offset0:132 offset1:134
	v_sub_f32_e32 v36, v47, v49
	v_exp_f32_e32 v47, v36
	v_cvt_pk_bf16_f32 v36, v57, v58
	v_cvt_pk_bf16_f32 v37, v60, v61
	v_cvt_pk_bf16_f32 v38, v62, v45
	v_cvt_pk_bf16_f32 v39, v46, v47
	s_waitcnt lgkmcnt(1)
	s_nop 0
	v_mfma_f32_32x32x16_bf16 v[16:31], v[32:35], v[36:39], v[16:31]
	v_add_f32_e32 v32, v60, v59
	v_add_f32_e32 v32, v61, v32
	v_add_f32_e32 v32, v62, v32
	v_add_f32_e32 v32, v45, v32
	v_add_f32_e32 v32, v46, v32
	v_add_f32_e32 v32, v47, v32
	v_fmac_f32_e32 v32, v155, v44
	s_waitcnt lgkmcnt(0)
	v_mfma_f32_32x32x16_bf16 v[0:15], v[40:43], v[36:39], v[0:15]
	v_mov_b32_e32 v155, v32
	s_andn2_b64 exec, exec, s[40:41]
	s_cbranch_execz .LBB0_376
